# GLA prep chunk data stored write-through (sc1) and the per-item agent release fence (buffer_wbl2) dropped
# speedup vs baseline: 1.0156x; 1.0156x over previous
.LBB0_629:
	s_or_b64 exec, exec, s[38:39]
	s_nop 5
	v_cvt_pk_bf16_f32 v0, v0, s0
	v_cndmask_b32_e64 v0, v0, 0, s[26:27]
	ds_write_b16 v66, v0
	v_cvt_pk_bf16_f32 v0, v1, s0
	v_cndmask_b32_e64 v0, v0, 0, s[28:29]
	ds_write_b16 v67, v0
	v_cvt_pk_bf16_f32 v0, v2, s0
	s_lshl_b64 s[38:39], s[58:59], 8
	v_cndmask_b32_e64 v0, v0, 0, s[30:31]
	v_mov_b32_e32 v5, s39
	v_or_b32_e32 v4, s38, v6
	ds_write_b16 v68, v0
	v_cvt_pk_bf16_f32 v0, v3, s0
	v_lshl_add_u64 v[84:85], v[4:5], 0, v[34:35]
	v_cndmask_b32_e64 v0, v0, 0, s[34:35]
	v_lshlrev_b64 v[84:85], 7, v[84:85]
	ds_write_b16 v69, v0
	v_lshl_add_u64 v[84:85], v[48:49], 0, v[84:85]
	v_lshl_add_u64 v[4:5], v[4:5], 0, v[36:37]
	ds_read_b64_tr_b16 v[0:1], v70
	ds_read_b64_tr_b16 v[2:3], v70 offset:2176
	s_waitcnt lgkmcnt(0)
	global_store_dwordx4 v[84:85], v[0:3], off sc1
	v_lshlrev_b64 v[4:5], 7, v[4:5]
	v_lshl_add_u64 v[4:5], v[48:49], 0, v[4:5]
	ds_read_b64_tr_b16 v[0:1], v71
	ds_read_b64_tr_b16 v[2:3], v71 offset:2176
	s_waitcnt lgkmcnt(0)
	global_store_dwordx4 v[84:85], v[0:3], off offset:64 sc1
	v_or_b32_e32 v54, v54, v6
	s_lshl_b32 s38, s91, 8
	ds_read_b64_tr_b16 v[0:1], v72
	ds_read_b64_tr_b16 v[2:3], v72 offset:2176
	s_waitcnt lgkmcnt(0)
	global_store_dwordx4 v[4:5], v[0:3], off sc1
	s_lshl_b32 s52, s38, 2
	v_mov_b32_e32 v51, v9
	ds_read_b64_tr_b16 v[0:1], v73
	ds_read_b64_tr_b16 v[2:3], v73 offset:2176
	s_waitcnt lgkmcnt(0)
	global_store_dwordx4 v[4:5], v[0:3], off offset:64 sc1
	s_waitcnt lgkmcnt(0)
	s_barrier
	ds_read_b128 v[0:3], v74
	ds_read_b64_tr_b16 v[114:115], v75 offset:0
	ds_read_b64_tr_b16 v[110:111], v75 offset:32
	ds_read_b64_tr_b16 v[106:107], v75 offset:64
	ds_read_b64_tr_b16 v[102:103], v75 offset:96
	ds_read_b64_tr_b16 v[98:99], v75 offset:128
	ds_read_b64_tr_b16 v[92:93], v75 offset:160
	ds_read_b64_tr_b16 v[88:89], v75 offset:192
	ds_read_b64_tr_b16 v[84:85], v75 offset:224
	ds_read_b64_tr_b16 v[116:117], v75 offset:2176
	ds_read_b64_tr_b16 v[112:113], v75 offset:2208
	ds_read_b64_tr_b16 v[108:109], v75 offset:2240
	ds_read_b64_tr_b16 v[104:105], v75 offset:2272
	ds_read_b64_tr_b16 v[100:101], v75 offset:2304
	ds_read_b64_tr_b16 v[94:95], v75 offset:2336
	ds_read_b64_tr_b16 v[90:91], v75 offset:2368
	ds_read_b64_tr_b16 v[86:87], v75 offset:2400
	s_waitcnt lgkmcnt(0)
	v_lshlrev_b64 v[4:5], 12, v[54:55]
	s_waitcnt lgkmcnt(0)
	v_mfma_f32_16x16x32_bf16 v[114:117], v[114:117], v[0:3], 0
	v_lshl_add_u64 v[4:5], s[56:57], 0, v[4:5]
	v_lshl_add_u64 v[4:5], v[4:5], 0, s[52:53]
	v_lshl_add_u64 v[4:5], v[4:5], 0, v[50:51]
	v_mfma_f32_16x16x32_bf16 v[110:113], v[110:113], v[0:3], 0
	v_mov_b32_e32 v53, v9
	v_lshl_add_u64 v[4:5], v[4:5], 0, v[52:53]
	s_lshl_b32 s38, s90, 3
	v_mfma_f32_16x16x32_bf16 v[106:109], v[106:109], v[0:3], 0
	s_add_i32 s52, s38, s89
	s_mov_b64 s[38:39], 0
	v_mfma_f32_16x16x32_bf16 v[102:105], v[102:105], v[0:3], 0
	v_mfma_f32_16x16x32_bf16 v[98:101], v[98:101], v[0:3], 0
	v_mfma_f32_16x16x32_bf16 v[92:95], v[92:95], v[0:3], 0
	v_mfma_f32_16x16x32_bf16 v[88:91], v[88:91], v[0:3], 0
	v_mfma_f32_16x16x32_bf16 v[0:3], v[84:87], v[0:3], 0
	ds_read_b128 v[84:87], v74 offset:64
	ds_read_b64_tr_b16 v[148:149], v76 offset:0
	ds_read_b64_tr_b16 v[144:145], v76 offset:32
	ds_read_b64_tr_b16 v[140:141], v76 offset:64
	ds_read_b64_tr_b16 v[136:137], v76 offset:96
	ds_read_b64_tr_b16 v[130:131], v76 offset:128
	ds_read_b64_tr_b16 v[126:127], v76 offset:160
	ds_read_b64_tr_b16 v[122:123], v76 offset:192
	ds_read_b64_tr_b16 v[118:119], v76 offset:224
	ds_read_b64_tr_b16 v[150:151], v76 offset:2176
	ds_read_b64_tr_b16 v[146:147], v76 offset:2208
	ds_read_b64_tr_b16 v[142:143], v76 offset:2240
	ds_read_b64_tr_b16 v[138:139], v76 offset:2272
	ds_read_b64_tr_b16 v[132:133], v76 offset:2304
	ds_read_b64_tr_b16 v[128:129], v76 offset:2336
	ds_read_b64_tr_b16 v[124:125], v76 offset:2368
	ds_read_b64_tr_b16 v[120:121], v76 offset:2400
	s_waitcnt lgkmcnt(0)
	s_waitcnt lgkmcnt(0)
	v_mfma_f32_16x16x32_bf16 v[114:117], v[148:151], v[84:87], v[114:117]
	v_mfma_f32_16x16x32_bf16 v[110:113], v[144:147], v[84:87], v[110:113]
	s_nop 6
	global_store_dwordx4 v[4:5], v[114:117], off
	v_mfma_f32_16x16x32_bf16 v[106:109], v[140:143], v[84:87], v[106:109]
	v_mfma_f32_16x16x32_bf16 v[102:105], v[136:139], v[84:87], v[102:105]
	v_mfma_f32_16x16x32_bf16 v[98:101], v[130:133], v[84:87], v[98:101]
	v_mfma_f32_16x16x32_bf16 v[92:95], v[126:129], v[84:87], v[92:95]
	v_mfma_f32_16x16x32_bf16 v[88:91], v[122:125], v[84:87], v[88:91]
	v_mfma_f32_16x16x32_bf16 v[0:3], v[118:121], v[84:87], v[0:3]
	global_store_dwordx4 v[4:5], v[110:113], off offset:64
	s_nop 1
	global_store_dwordx4 v[4:5], v[106:109], off offset:128
	global_store_dwordx4 v[4:5], v[102:105], off offset:192
	global_store_dwordx4 v[4:5], v[98:101], off offset:256
	global_store_dwordx4 v[4:5], v[92:95], off offset:320
	global_store_dwordx4 v[4:5], v[88:91], off offset:384
	global_store_dwordx4 v[4:5], v[0:3], off offset:448
	s_waitcnt vmcnt(0)
	s_barrier

.LBB0_631:
	s_and_saveexec_b64 s[38:39], s[36:37]
	s_cbranch_execz .LBB0_639
	s_cmp_lt_i32 s52, 0
	s_cbranch_scc1 .LBB0_636
	s_mov_b64 s[58:59], exec
	s_waitcnt vmcnt(0) lgkmcnt(0)
	s_waitcnt vmcnt(0)
	v_mbcnt_lo_u32_b32 v0, s58, 0
	v_mbcnt_hi_u32_b32 v0, s59, v0
	v_cmp_eq_u32_e32 vcc, 0, v0
	s_and_saveexec_b64 s[60:61], vcc
	s_cbranch_execz .LBB0_635
	s_lshl_b64 s[90:91], s[52:53], 2
	s_add_u32 s90, s3, s90
	s_addc_u32 s91, s33, s91
	s_bcnt1_i32_b64 s52, s[58:59]
	v_mov_b32_e32 v0, s52
	global_atomic_add v9, v0, s[90:91]

.LBB0_642:
	s_or_b64 exec, exec, s[38:39]
	v_or_b32_e32 v92, s60, v10
	v_mov_b64_e32 v[54:55], s[54:55]
	v_or_b32_e32 v94, s60, v12
	s_mul_i32 s92, s61, 0x3200
	v_mad_u64_u32 v[92:93], s[38:39], v92, s66, v[54:55]
	v_mad_u64_u32 v[94:95], s[38:39], v94, s66, v[54:55]
	v_add_u32_e32 v93, s92, v93
	s_lshl_b32 s52, s91, 9
	v_add_u32_e32 v95, s92, v95
	v_lshl_add_u64 v[92:93], v[92:93], 0, s[52:53]
	v_lshl_add_u64 v[94:95], v[94:95], 0, s[52:53]
	v_lshl_add_u64 v[92:93], v[92:93], 0, v[8:9]
	v_lshl_add_u64 v[94:95], v[94:95], 0, v[8:9]
	global_load_dwordx4 v[104:107], v[92:93], off offset:2048
	global_load_dwordx4 v[108:111], v[94:95], off offset:2048
	v_or_b32_e32 v92, s60, v14
	v_lshl_add_u64 v[94:95], s[60:61], 0, v[16:17]
	v_mad_u64_u32 v[92:93], s[38:39], v92, s66, v[54:55]
	v_mad_u64_u32 v[54:55], s[38:39], v94, s66, v[54:55]
	v_mov_b32_e32 v94, v55
	v_add_u32_e32 v93, s92, v93
	v_mad_u64_u32 v[94:95], s[38:39], v95, s66, v[94:95]
	v_lshl_add_u64 v[92:93], v[92:93], 0, s[52:53]
	v_mov_b32_e32 v55, v94
	v_lshl_add_u64 v[92:93], v[92:93], 0, v[8:9]
	v_lshl_add_u64 v[54:55], v[54:55], 0, s[52:53]
	v_lshl_add_u64 v[54:55], v[54:55], 0, v[8:9]
	global_load_dwordx4 v[112:115], v[92:93], off offset:2048
	global_load_dwordx4 v[116:119], v[54:55], off offset:2048
	s_lshl_b32 s52, s59, 1
	v_lshl_add_u64 v[54:55], s[60:61], 0, v[18:19]
	v_lshl_add_u64 v[92:93], v[40:41], 0, s[52:53]
	v_mad_u64_u32 v[120:121], s[38:39], v54, s66, v[92:93]
	v_mov_b32_e32 v92, v121
	v_mad_u64_u32 v[122:123], s[38:39], v55, s66, v[92:93]
	v_add_co_u32_e32 v92, vcc, s64, v120
	v_mov_b32_e32 v121, v122
	s_nop 0
	v_addc_co_u32_e32 v93, vcc, 0, v122, vcc
	v_add_co_u32_e32 v94, vcc, s65, v120
	s_ashr_i32 s59, s58, 31
	s_nop 0
	v_addc_co_u32_e32 v95, vcc, 0, v122, vcc
	v_add_co_u32_e32 v124, vcc, s67, v120
	s_nop 1
	v_addc_co_u32_e32 v125, vcc, 0, v122, vcc
	v_add_co_u32_e32 v126, vcc, s68, v120
	s_nop 1
	v_addc_co_u32_e32 v127, vcc, 0, v122, vcc
	v_add_co_u32_e32 v128, vcc, s69, v120
	global_load_ushort v102, v[92:93], off offset:512
	global_load_ushort v101, v[92:93], off offset:1536
	global_load_ushort v97, v[94:95], off offset:1024
	s_nop 0
	global_load_ushort v93, v[94:95], off offset:2048
	global_load_ushort v98, v[124:125], off offset:1536
	s_nop 0
	global_load_ushort v95, v[124:125], off offset:2560
	global_load_ushort v94, v[126:127], off offset:2048
	global_load_ushort v92, v[126:127], off offset:3072
	v_addc_co_u32_e32 v129, vcc, 0, v122, vcc
	v_add_co_u32_e32 v130, vcc, s70, v120
	s_waitcnt vmcnt(11)
	ds_write_b128 v77, v[104:107] offset:34816
	s_waitcnt vmcnt(10)
	ds_write_b128 v78, v[108:111] offset:34816
	s_waitcnt vmcnt(9)
	ds_write_b128 v77, v[112:115] offset:52224
	s_waitcnt vmcnt(8)
	ds_write_b128 v79, v[116:119] offset:34816
	v_addc_co_u32_e32 v131, vcc, 0, v122, vcc
	v_add_co_u32_e32 v132, vcc, s71, v120
	s_nop 1
	v_addc_co_u32_e32 v133, vcc, 0, v122, vcc
	v_add_co_u32_e32 v136, vcc, s72, v120
	s_nop 1
	v_addc_co_u32_e32 v137, vcc, 0, v122, vcc
	v_add_co_u32_e32 v110, vcc, s73, v120
	s_nop 1
	v_addc_co_u32_e32 v111, vcc, 0, v122, vcc
	v_add_co_u32_e32 v112, vcc, s74, v120
	s_nop 1
	v_addc_co_u32_e32 v113, vcc, 0, v122, vcc
	global_load_ushort v108, v[128:129], off offset:2560
	global_load_ushort v107, v[128:129], off offset:3584
	global_load_ushort v105, v[130:131], off offset:3072
	global_load_ushort v100, v[132:133], off
	global_load_ushort v106, v[136:137], off offset:3584
	global_load_ushort v104, v[110:111], off offset:512
	global_load_ushort v103, v[112:113], off
	global_load_ushort v99, v[112:113], off offset:1024
	v_add_co_u32_e32 v110, vcc, s75, v120
	s_nop 1
	v_addc_co_u32_e32 v111, vcc, 0, v122, vcc
	v_add_co_u32_e32 v118, vcc, s76, v120
	s_nop 1
	v_addc_co_u32_e32 v119, vcc, 0, v122, vcc
	v_add_co_u32_e32 v124, vcc, s77, v120
	s_nop 1
	v_addc_co_u32_e32 v125, vcc, 0, v122, vcc
	v_add_co_u32_e32 v126, vcc, s78, v120
	s_nop 1
	v_addc_co_u32_e32 v127, vcc, 0, v122, vcc
	global_load_ushort v116, v[110:111], off offset:512
	global_load_ushort v115, v[110:111], off offset:1536
	global_load_ushort v113, v[118:119], off offset:1024
	s_nop 0
	global_load_ushort v110, v[118:119], off offset:2048
	global_load_ushort v114, v[124:125], off offset:1536
	global_load_ushort v112, v[124:125], off offset:2560
	global_load_ushort v111, v[126:127], off offset:2048
	global_load_ushort v109, v[126:127], off offset:3072
	v_add_co_u32_e32 v118, vcc, s79, v120
	s_nop 1
	v_addc_co_u32_e32 v119, vcc, 0, v122, vcc
	v_add_co_u32_e32 v126, vcc, s80, v120
	s_nop 1
	v_addc_co_u32_e32 v127, vcc, 0, v122, vcc
	v_add_co_u32_e32 v128, vcc, s81, v120
	s_nop 1
	v_addc_co_u32_e32 v129, vcc, 0, v122, vcc
	v_add_co_u32_e32 v130, vcc, s82, v120
	s_nop 1
	v_addc_co_u32_e32 v131, vcc, 0, v122, vcc
	v_add_co_u32_e32 v132, vcc, s83, v120
	s_nop 1
	v_addc_co_u32_e32 v133, vcc, 0, v122, vcc
	global_load_ushort v124, v[120:121], off
	global_load_ushort v123, v[120:121], off offset:1024
	global_load_ushort v122, v[118:119], off offset:2560
	s_nop 0
	global_load_ushort v121, v[118:119], off offset:3584
	s_nop 0
	global_load_ushort v118, v[126:127], off offset:3072
	global_load_ushort v117, v[128:129], off
	global_load_ushort v119, v[130:131], off offset:3584
	global_load_ushort v120, v[132:133], off offset:512
	s_waitcnt lgkmcnt(0)
	s_barrier
	ds_read_b128 v[126:129], v13
	ds_read_b128 v[130:133], v13 offset:16
	ds_read_b128 v[136:139], v13 offset:32
	ds_read_b128 v[140:143], v13 offset:48
	s_waitcnt lgkmcnt(3)
	v_fma_f32 v125, v91, v126, v3
	v_fmac_f32_e32 v125, v0, v127
	v_fmac_f32_e32 v125, v83, v128
	v_fmac_f32_e32 v125, v84, v129
	s_waitcnt lgkmcnt(2)
	v_fmac_f32_e32 v125, v53, v130
	v_fmac_f32_e32 v125, v4, v131
	v_fmac_f32_e32 v125, v5, v132
	v_fmac_f32_e32 v125, v51, v133
	s_waitcnt lgkmcnt(1)
	v_fmac_f32_e32 v125, v1, v136
	v_fmac_f32_e32 v125, v2, v137
	v_fmac_f32_e32 v125, v88, v138
	v_fmac_f32_e32 v125, v89, v139
	s_waitcnt lgkmcnt(0)
	v_fmac_f32_e32 v125, v86, v140
	v_fmac_f32_e32 v125, v85, v141
	v_fmac_f32_e32 v125, v87, v142
	v_fmac_f32_e32 v125, v90, v143
	v_mul_f32_e64 v126, |v125|, s84
	v_exp_f32_e32 v126, v126
	v_min_f32_e32 v125, 0, v125
	v_add_f32_e32 v126, 1.0, v126
	v_cmp_gt_f32_e32 vcc, s85, v126
	s_nop 1
	v_cndmask_b32_e64 v127, 0, 32, vcc
	v_ldexp_f32 v126, v126, v127
	v_log_f32_e32 v135, v126
	ds_read_b128 v[126:129], v13 offset:64
	v_mul_f32_e32 v130, 0x3f317217, v135
	v_fma_f32 v136, v135, s86, -v130
	ds_read_b128 v[130:133], v13 offset:80
	s_waitcnt lgkmcnt(1)
	v_fma_f32 v137, v91, v126, v3
	v_fmac_f32_e32 v137, v0, v127
	v_fmac_f32_e32 v137, v83, v128
	v_fmac_f32_e32 v137, v84, v129
	ds_read_b128 v[126:129], v13 offset:96
	s_waitcnt lgkmcnt(1)
	v_fmac_f32_e32 v137, v53, v130
	v_fmac_f32_e32 v137, v4, v131
	v_fmac_f32_e32 v137, v5, v132
	v_fmac_f32_e32 v137, v51, v133
	ds_read_b128 v[130:133], v13 offset:112
	s_waitcnt lgkmcnt(1)
	v_fmac_f32_e32 v137, v1, v126
	v_fmac_f32_e32 v137, v2, v127
	v_fmac_f32_e32 v137, v88, v128
	v_fmac_f32_e32 v137, v89, v129
	s_waitcnt lgkmcnt(0)
	v_fmac_f32_e32 v137, v86, v130
	v_fmac_f32_e32 v137, v85, v131
	v_fmac_f32_e32 v137, v87, v132
	v_fmac_f32_e32 v137, v90, v133
	v_mul_f32_e64 v126, |v137|, s84
	v_exp_f32_e32 v126, v126
	v_fmac_f32_e32 v136, 0x3377d1cf, v135
	v_fmac_f32_e32 v136, 0x3f317217, v135
	v_cmp_lt_f32_e64 s[38:39], |v135|, s87
	v_add_f32_e32 v126, 1.0, v126
	v_cndmask_b32_e32 v128, 0, v81, vcc
	v_cndmask_b32_e64 v127, v135, v136, s[38:39]
	v_cmp_gt_f32_e32 vcc, s85, v126
	v_sub_f32_e32 v127, v127, v128
	v_sub_f32_e32 v125, v125, v127
	v_cndmask_b32_e64 v128, 0, 32, vcc
	v_ldexp_f32 v126, v126, v128
	v_log_f32_e32 v135, v126
	ds_read_b128 v[126:129], v13 offset:128
	v_min_f32_e32 v136, 0, v137
	v_fma_f32 v125, v125, s88, 0
	v_mul_f32_e32 v130, 0x3f317217, v135
	v_fma_f32 v137, v135, s86, -v130
	ds_read_b128 v[130:133], v13 offset:144
	s_waitcnt lgkmcnt(1)
	v_fma_f32 v138, v91, v126, v3
	v_fmac_f32_e32 v138, v0, v127
	v_fmac_f32_e32 v138, v83, v128
	v_fmac_f32_e32 v138, v84, v129
	ds_read_b128 v[126:129], v13 offset:160
	s_waitcnt lgkmcnt(1)
	v_fmac_f32_e32 v138, v53, v130
	v_fmac_f32_e32 v138, v4, v131
	v_fmac_f32_e32 v138, v5, v132
	v_fmac_f32_e32 v138, v51, v133
	ds_read_b128 v[130:133], v13 offset:176
	s_waitcnt lgkmcnt(1)
	v_fmac_f32_e32 v138, v1, v126
	v_fmac_f32_e32 v138, v2, v127
	v_fmac_f32_e32 v138, v88, v128
	v_fmac_f32_e32 v138, v89, v129
	s_waitcnt lgkmcnt(0)
	v_fmac_f32_e32 v138, v86, v130
	v_fmac_f32_e32 v138, v85, v131
	v_fmac_f32_e32 v138, v87, v132
	v_fmac_f32_e32 v138, v90, v133
	v_mul_f32_e64 v126, |v138|, s84
	v_exp_f32_e32 v126, v126
	v_fmac_f32_e32 v137, 0x3377d1cf, v135
	v_fmac_f32_e32 v137, 0x3f317217, v135
	v_cmp_lt_f32_e64 s[38:39], |v135|, s87
	v_add_f32_e32 v126, 1.0, v126
	v_cndmask_b32_e32 v128, 0, v81, vcc
	v_cndmask_b32_e64 v127, v135, v137, s[38:39]
	v_cmp_gt_f32_e32 vcc, s85, v126
	v_sub_f32_e32 v127, v127, v128
	s_nop 0
	v_cndmask_b32_e64 v128, 0, 32, vcc
	v_ldexp_f32 v126, v126, v128
	ds_read_b128 v[128:131], v13 offset:192
	v_log_f32_e32 v132, v126
	v_sub_f32_e32 v126, v136, v127
	v_min_f32_e32 v127, 0, v138
	ds_read_b128 v[136:139], v13 offset:208
	s_waitcnt lgkmcnt(1)
	v_fma_f32 v135, v91, v128, v3
	v_fmac_f32_e32 v135, v0, v129
	v_fmac_f32_e32 v135, v83, v130
	v_fmac_f32_e32 v135, v84, v131
	ds_read_b128 v[128:131], v13 offset:224
	s_waitcnt lgkmcnt(1)
	v_fmac_f32_e32 v135, v53, v136
	v_fmac_f32_e32 v135, v4, v137
	v_fmac_f32_e32 v135, v5, v138
	v_fmac_f32_e32 v135, v51, v139
	ds_read_b128 v[136:139], v13 offset:240
	s_waitcnt lgkmcnt(1)
	v_fmac_f32_e32 v135, v1, v128
	v_fmac_f32_e32 v135, v2, v129
	v_fmac_f32_e32 v135, v88, v130
	v_fmac_f32_e32 v135, v89, v131
	s_waitcnt lgkmcnt(0)
	v_fmac_f32_e32 v135, v86, v136
	v_fmac_f32_e32 v135, v85, v137
	v_fmac_f32_e32 v135, v87, v138
	v_fmac_f32_e32 v135, v90, v139
	v_mul_f32_e64 v128, |v135|, s84
	v_exp_f32_e32 v128, v128
	v_mul_f32_e32 v133, 0x3f317217, v132
	v_fma_f32 v133, v132, s86, -v133
	v_fmac_f32_e32 v133, 0x3377d1cf, v132
	v_fmac_f32_e32 v133, 0x3f317217, v132
	v_cmp_lt_f32_e64 s[38:39], |v132|, s87
	v_add_f32_e32 v128, 1.0, v128
	v_cndmask_b32_e32 v130, 0, v81, vcc
	v_cndmask_b32_e64 v129, v132, v133, s[38:39]
	v_cmp_gt_f32_e32 vcc, s85, v128
	v_sub_f32_e32 v129, v129, v130
	v_sub_f32_e32 v127, v127, v129
	v_cndmask_b32_e64 v130, 0, 32, vcc
	v_ldexp_f32 v128, v128, v130
	v_log_f32_e32 v132, v128
	ds_read_b128 v[128:131], v13 offset:256
	ds_read_b128 v[136:139], v13 offset:272
	v_min_f32_e32 v133, 0, v135
	v_mul_f32_e32 v135, 0x3f317217, v132
	v_fma_f32 v135, v132, s86, -v135
	s_waitcnt lgkmcnt(1)
	v_fma_f32 v140, v91, v128, v3
	v_fmac_f32_e32 v140, v0, v129
	v_fmac_f32_e32 v140, v83, v130
	v_fmac_f32_e32 v140, v84, v131
	ds_read_b128 v[128:131], v13 offset:288
	s_waitcnt lgkmcnt(1)
	v_fmac_f32_e32 v140, v53, v136
	v_fmac_f32_e32 v140, v4, v137
	v_fmac_f32_e32 v140, v5, v138
	v_fmac_f32_e32 v140, v51, v139
	ds_read_b128 v[136:139], v13 offset:304
	s_waitcnt lgkmcnt(1)
	v_fmac_f32_e32 v140, v1, v128
	v_fmac_f32_e32 v140, v2, v129
	v_fmac_f32_e32 v140, v88, v130
	v_fmac_f32_e32 v140, v89, v131
	s_waitcnt lgkmcnt(0)
	v_fmac_f32_e32 v140, v86, v136
	v_fmac_f32_e32 v140, v85, v137
	v_fmac_f32_e32 v140, v87, v138
	v_fmac_f32_e32 v140, v90, v139
	v_mul_f32_e64 v128, |v140|, s84
	v_exp_f32_e32 v128, v128
	v_fmac_f32_e32 v135, 0x3377d1cf, v132
	v_fmac_f32_e32 v135, 0x3f317217, v132
	v_cmp_lt_f32_e64 s[38:39], |v132|, s87
	v_add_f32_e32 v128, 1.0, v128
	v_cndmask_b32_e32 v130, 0, v81, vcc
	v_cndmask_b32_e64 v129, v132, v135, s[38:39]
	v_cmp_gt_f32_e32 vcc, s85, v128
	v_sub_f32_e32 v129, v129, v130
	v_fmamk_f32 v126, v126, 0x3d800000, v125
	v_cndmask_b32_e64 v130, 0, 32, vcc
	v_ldexp_f32 v128, v128, v130
	v_log_f32_e32 v135, v128
	v_sub_f32_e32 v128, v133, v129
	ds_read_b128 v[130:133], v13 offset:320
	v_min_f32_e32 v129, 0, v140
	v_mul_f32_e32 v136, 0x3f317217, v135
	v_fma_f32 v140, v135, s86, -v136
	ds_read_b128 v[136:139], v13 offset:336
	s_waitcnt lgkmcnt(1)
	v_fma_f32 v141, v91, v130, v3
	v_fmac_f32_e32 v141, v0, v131
	v_fmac_f32_e32 v141, v83, v132
	v_fmac_f32_e32 v141, v84, v133
	ds_read_b128 v[130:133], v13 offset:352
	s_waitcnt lgkmcnt(1)
	v_fmac_f32_e32 v141, v53, v136
	v_fmac_f32_e32 v141, v4, v137
	v_fmac_f32_e32 v141, v5, v138
	v_fmac_f32_e32 v141, v51, v139
	ds_read_b128 v[136:139], v13 offset:368
	s_waitcnt lgkmcnt(1)
	v_fmac_f32_e32 v141, v1, v130
	v_fmac_f32_e32 v141, v2, v131
	v_fmac_f32_e32 v141, v88, v132
	v_fmac_f32_e32 v141, v89, v133
	s_waitcnt lgkmcnt(0)
	v_fmac_f32_e32 v141, v86, v136
	v_fmac_f32_e32 v141, v85, v137
	v_fmac_f32_e32 v141, v87, v138
	v_fmac_f32_e32 v141, v90, v139
	v_mul_f32_e64 v130, |v141|, s84
	v_exp_f32_e32 v130, v130
	v_fmac_f32_e32 v140, 0x3377d1cf, v135
	v_fmac_f32_e32 v140, 0x3f317217, v135
	v_cmp_lt_f32_e64 s[38:39], |v135|, s87
	v_add_f32_e32 v130, 1.0, v130
	v_cndmask_b32_e32 v132, 0, v81, vcc
	v_cndmask_b32_e64 v131, v135, v140, s[38:39]
	v_cmp_gt_f32_e32 vcc, s85, v130
	v_sub_f32_e32 v131, v131, v132
	v_sub_f32_e32 v129, v129, v131
	v_cndmask_b32_e64 v132, 0, 32, vcc
	v_ldexp_f32 v130, v130, v132
	v_log_f32_e32 v135, v130
	ds_read_b128 v[130:133], v13 offset:384
	v_min_f32_e32 v140, 0, v141
	v_fmamk_f32 v127, v127, 0x3d800000, v126
	v_mul_f32_e32 v136, 0x3f317217, v135
	v_fma_f32 v141, v135, s86, -v136
	ds_read_b128 v[136:139], v13 offset:400
	s_waitcnt lgkmcnt(1)
	v_fma_f32 v142, v91, v130, v3
	v_fmac_f32_e32 v142, v0, v131
	v_fmac_f32_e32 v142, v83, v132
	v_fmac_f32_e32 v142, v84, v133
	ds_read_b128 v[130:133], v13 offset:416
	s_waitcnt lgkmcnt(1)
	v_fmac_f32_e32 v142, v53, v136
	v_fmac_f32_e32 v142, v4, v137
	v_fmac_f32_e32 v142, v5, v138
	v_fmac_f32_e32 v142, v51, v139
	ds_read_b128 v[136:139], v13 offset:432
	s_waitcnt lgkmcnt(1)
	v_fmac_f32_e32 v142, v1, v130
	v_fmac_f32_e32 v142, v2, v131
	v_fmac_f32_e32 v142, v88, v132
	v_fmac_f32_e32 v142, v89, v133
	s_waitcnt lgkmcnt(0)
	v_fmac_f32_e32 v142, v86, v136
	v_fmac_f32_e32 v142, v85, v137
	v_fmac_f32_e32 v142, v87, v138
	v_fmac_f32_e32 v142, v90, v139
	v_mul_f32_e64 v130, |v142|, s84
	v_exp_f32_e32 v130, v130
	v_fmac_f32_e32 v141, 0x3377d1cf, v135
	v_fmac_f32_e32 v141, 0x3f317217, v135
	v_cmp_lt_f32_e64 s[38:39], |v135|, s87
	v_add_f32_e32 v130, 1.0, v130
	ds_read_b128 v[136:139], v13 offset:448
	v_cndmask_b32_e64 v131, v135, v141, s[38:39]
	v_cndmask_b32_e32 v132, 0, v81, vcc
	v_cmp_gt_f32_e32 vcc, s85, v130
	v_sub_f32_e32 v131, v131, v132
	v_fmamk_f32 v128, v128, 0x3d800000, v127
	v_cndmask_b32_e64 v132, 0, 32, vcc
	v_ldexp_f32 v130, v130, v132
	v_log_f32_e32 v132, v130
	v_sub_f32_e32 v130, v140, v131
	v_min_f32_e32 v131, 0, v142
	ds_read_b128 v[140:143], v13 offset:464
	s_waitcnt lgkmcnt(1)
	v_fma_f32 v135, v91, v136, v3
	v_fmac_f32_e32 v135, v0, v137
	v_fmac_f32_e32 v135, v83, v138
	v_fmac_f32_e32 v135, v84, v139
	ds_read_b128 v[136:139], v13 offset:480
	s_waitcnt lgkmcnt(1)
	v_fmac_f32_e32 v135, v53, v140
	v_fmac_f32_e32 v135, v4, v141
	v_fmac_f32_e32 v135, v5, v142
	v_fmac_f32_e32 v135, v51, v143
	ds_read_b128 v[140:143], v13 offset:496
	s_waitcnt lgkmcnt(1)
	v_fmac_f32_e32 v135, v1, v136
	v_fmac_f32_e32 v135, v2, v137
	v_fmac_f32_e32 v135, v88, v138
	v_fmac_f32_e32 v135, v89, v139
	s_waitcnt lgkmcnt(0)
	v_fmac_f32_e32 v135, v86, v140
	v_fmac_f32_e32 v135, v85, v141
	v_fmac_f32_e32 v135, v87, v142
	v_fmac_f32_e32 v135, v90, v143
	v_mul_f32_e32 v133, 0x3f317217, v132
	v_mul_f32_e64 v136, |v135|, s84
	v_fma_f32 v133, v132, s86, -v133
	v_exp_f32_e32 v136, v136
	v_fmac_f32_e32 v133, 0x3377d1cf, v132
	v_fmac_f32_e32 v133, 0x3f317217, v132
	v_cmp_lt_f32_e64 s[38:39], |v132|, s87
	ds_read_b128 v[140:143], v13 offset:528
	v_fmamk_f32 v129, v129, 0x3d800000, v128
	v_cndmask_b32_e64 v132, v132, v133, s[38:39]
	v_cndmask_b32_e32 v133, 0, v81, vcc
	v_sub_f32_e32 v132, v132, v133
	v_add_f32_e32 v133, 1.0, v136
	v_cmp_gt_f32_e32 vcc, s85, v133
	v_sub_f32_e32 v131, v131, v132
	v_min_f32_e32 v132, 0, v135
	v_cndmask_b32_e64 v136, 0, 32, vcc
	v_ldexp_f32 v133, v133, v136
	ds_read_b128 v[136:139], v13 offset:512
	v_log_f32_e32 v133, v133
	v_fmamk_f32 v130, v130, 0x3d800000, v129
	v_fmamk_f32 v131, v131, 0x3d800000, v130
	s_waitcnt lgkmcnt(0)
	v_fma_f32 v144, v91, v136, v3
	v_fmac_f32_e32 v144, v0, v137
	v_fmac_f32_e32 v144, v83, v138
	v_fmac_f32_e32 v144, v84, v139
	ds_read_b128 v[136:139], v13 offset:544
	v_fmac_f32_e32 v144, v53, v140
	v_fmac_f32_e32 v144, v4, v141
	v_fmac_f32_e32 v144, v5, v142
	v_fmac_f32_e32 v144, v51, v143
	ds_read_b128 v[140:143], v13 offset:560
	s_waitcnt lgkmcnt(1)
	v_fmac_f32_e32 v144, v1, v136
	v_fmac_f32_e32 v144, v2, v137
	v_fmac_f32_e32 v144, v88, v138
	v_fmac_f32_e32 v144, v89, v139
	s_waitcnt lgkmcnt(0)
	v_fmac_f32_e32 v144, v86, v140
	v_fmac_f32_e32 v144, v85, v141
	v_fmac_f32_e32 v144, v87, v142
	v_fmac_f32_e32 v144, v90, v143
	v_mul_f32_e32 v135, 0x3f317217, v133
	v_mul_f32_e64 v136, |v144|, s84
	v_fma_f32 v135, v133, s86, -v135
	v_exp_f32_e32 v136, v136
	v_fmac_f32_e32 v135, 0x3377d1cf, v133
	v_fmac_f32_e32 v135, 0x3f317217, v133
	v_cmp_lt_f32_e64 s[38:39], |v133|, s87
	s_nop 1
	v_cndmask_b32_e64 v133, v133, v135, s[38:39]
	v_cndmask_b32_e32 v135, 0, v81, vcc
	v_sub_f32_e32 v133, v133, v135
	v_add_f32_e32 v135, 1.0, v136
	v_cmp_gt_f32_e32 vcc, s85, v135
	v_sub_f32_e32 v132, v132, v133
	v_min_f32_e32 v133, 0, v144
	v_cndmask_b32_e64 v136, 0, 32, vcc
	v_ldexp_f32 v135, v135, v136
	v_log_f32_e32 v135, v135
	ds_read_b128 v[136:139], v13 offset:576
	v_fmamk_f32 v132, v132, 0x3d800000, v131
	v_mul_f32_e32 v140, 0x3f317217, v135
	v_fma_f32 v144, v135, s86, -v140
	ds_read_b128 v[140:143], v13 offset:592
	s_waitcnt lgkmcnt(1)
	v_fma_f32 v145, v91, v136, v3
	v_fmac_f32_e32 v145, v0, v137
	v_fmac_f32_e32 v145, v83, v138
	v_fmac_f32_e32 v145, v84, v139
	ds_read_b128 v[136:139], v13 offset:608
	s_waitcnt lgkmcnt(1)
	v_fmac_f32_e32 v145, v53, v140
	v_fmac_f32_e32 v145, v4, v141
	v_fmac_f32_e32 v145, v5, v142
	v_fmac_f32_e32 v145, v51, v143
	ds_read_b128 v[140:143], v13 offset:624
	s_waitcnt lgkmcnt(1)
	v_fmac_f32_e32 v145, v1, v136
	v_fmac_f32_e32 v145, v2, v137
	v_fmac_f32_e32 v145, v88, v138
	v_fmac_f32_e32 v145, v89, v139
	s_waitcnt lgkmcnt(0)
	v_fmac_f32_e32 v145, v86, v140
	v_fmac_f32_e32 v145, v85, v141
	v_fmac_f32_e32 v145, v87, v142
	v_fmac_f32_e32 v145, v90, v143
	v_mul_f32_e64 v136, |v145|, s84
	v_exp_f32_e32 v136, v136
	v_fmac_f32_e32 v144, 0x3377d1cf, v135
	v_fmac_f32_e32 v144, 0x3f317217, v135
	v_cmp_lt_f32_e64 s[38:39], |v135|, s87
	v_add_f32_e32 v136, 1.0, v136
	v_cndmask_b32_e32 v137, 0, v81, vcc
	v_cndmask_b32_e64 v135, v135, v144, s[38:39]
	v_cmp_gt_f32_e32 vcc, s85, v136
	v_sub_f32_e32 v135, v135, v137
	v_sub_f32_e32 v133, v133, v135
	v_cndmask_b32_e64 v137, 0, 32, vcc
	v_ldexp_f32 v136, v136, v137
	v_log_f32_e32 v144, v136
	ds_read_b128 v[136:139], v13 offset:640
	v_min_f32_e32 v135, 0, v145
	v_fmamk_f32 v133, v133, 0x3d800000, v132
	v_mul_f32_e32 v140, 0x3f317217, v144
	v_fma_f32 v145, v144, s86, -v140
	ds_read_b128 v[140:143], v13 offset:656
	s_waitcnt lgkmcnt(1)
	v_fma_f32 v146, v91, v136, v3
	v_fmac_f32_e32 v146, v0, v137
	v_fmac_f32_e32 v146, v83, v138
	v_fmac_f32_e32 v146, v84, v139
	ds_read_b128 v[136:139], v13 offset:672
	s_waitcnt lgkmcnt(1)
	v_fmac_f32_e32 v146, v53, v140
	v_fmac_f32_e32 v146, v4, v141
	v_fmac_f32_e32 v146, v5, v142
	v_fmac_f32_e32 v146, v51, v143
	ds_read_b128 v[140:143], v13 offset:688
	s_waitcnt lgkmcnt(1)
	v_fmac_f32_e32 v146, v1, v136
	v_fmac_f32_e32 v146, v2, v137
	v_fmac_f32_e32 v146, v88, v138
	v_fmac_f32_e32 v146, v89, v139
	s_waitcnt lgkmcnt(0)
	v_fmac_f32_e32 v146, v86, v140
	v_fmac_f32_e32 v146, v85, v141
	v_fmac_f32_e32 v146, v87, v142
	v_fmac_f32_e32 v146, v90, v143
	v_mul_f32_e64 v136, |v146|, s84
	v_exp_f32_e32 v136, v136
	v_fmac_f32_e32 v145, 0x3377d1cf, v144
	v_fmac_f32_e32 v145, 0x3f317217, v144
	v_cmp_lt_f32_e64 s[38:39], |v144|, s87
	v_add_f32_e32 v136, 1.0, v136
	v_cndmask_b32_e32 v138, 0, v81, vcc
	v_cndmask_b32_e64 v137, v144, v145, s[38:39]
	v_cmp_gt_f32_e32 vcc, s85, v136
	v_sub_f32_e32 v137, v137, v138
	v_sub_f32_e32 v135, v135, v137
	v_cndmask_b32_e64 v138, 0, 32, vcc
	v_ldexp_f32 v136, v136, v138
	v_log_f32_e32 v144, v136
	ds_read_b128 v[136:139], v13 offset:704
	v_min_f32_e32 v145, 0, v146
	v_fmamk_f32 v135, v135, 0x3d800000, v133
	v_mul_f32_e32 v140, 0x3f317217, v144
	v_fma_f32 v146, v144, s86, -v140
	ds_read_b128 v[140:143], v13 offset:720
	s_waitcnt lgkmcnt(1)
	v_fma_f32 v147, v91, v136, v3
	v_fmac_f32_e32 v147, v0, v137
	v_fmac_f32_e32 v147, v83, v138
	v_fmac_f32_e32 v147, v84, v139
	ds_read_b128 v[136:139], v13 offset:736
	s_waitcnt lgkmcnt(1)
	v_fmac_f32_e32 v147, v53, v140
	v_fmac_f32_e32 v147, v4, v141
	v_fmac_f32_e32 v147, v5, v142
	v_fmac_f32_e32 v147, v51, v143
	ds_read_b128 v[140:143], v13 offset:752
	s_waitcnt lgkmcnt(1)
	v_fmac_f32_e32 v147, v1, v136
	v_fmac_f32_e32 v147, v2, v137
	v_fmac_f32_e32 v147, v88, v138
	v_fmac_f32_e32 v147, v89, v139
	s_waitcnt lgkmcnt(0)
	v_fmac_f32_e32 v147, v86, v140
	v_fmac_f32_e32 v147, v85, v141
	v_fmac_f32_e32 v147, v87, v142
	v_fmac_f32_e32 v147, v90, v143
	v_mul_f32_e64 v136, |v147|, s84
	v_exp_f32_e32 v136, v136
	v_fmac_f32_e32 v146, 0x3377d1cf, v144
	v_fmac_f32_e32 v146, 0x3f317217, v144
	v_cmp_lt_f32_e64 s[38:39], |v144|, s87
	v_add_f32_e32 v136, 1.0, v136
	v_cndmask_b32_e32 v138, 0, v81, vcc
	v_cndmask_b32_e64 v137, v144, v146, s[38:39]
	v_cmp_gt_f32_e32 vcc, s85, v136
	v_sub_f32_e32 v137, v137, v138
	s_nop 0
	v_cndmask_b32_e64 v138, 0, 32, vcc
	v_ldexp_f32 v136, v136, v138
	v_log_f32_e32 v146, v136
	ds_read_b128 v[138:141], v13 offset:768
	v_sub_f32_e32 v136, v145, v137
	v_min_f32_e32 v137, 0, v147
	v_mul_f32_e32 v142, 0x3f317217, v146
	v_fma_f32 v147, v146, s86, -v142
	ds_read_b128 v[142:145], v13 offset:784
	s_waitcnt lgkmcnt(1)
	v_fma_f32 v148, v91, v138, v3
	v_fmac_f32_e32 v148, v0, v139
	v_fmac_f32_e32 v148, v83, v140
	v_fmac_f32_e32 v148, v84, v141
	ds_read_b128 v[138:141], v13 offset:800
	s_waitcnt lgkmcnt(1)
	v_fmac_f32_e32 v148, v53, v142
	v_fmac_f32_e32 v148, v4, v143
	v_fmac_f32_e32 v148, v5, v144
	v_fmac_f32_e32 v148, v51, v145
	ds_read_b128 v[142:145], v13 offset:816
	s_waitcnt lgkmcnt(1)
	v_fmac_f32_e32 v148, v1, v138
	v_fmac_f32_e32 v148, v2, v139
	v_fmac_f32_e32 v148, v88, v140
	v_fmac_f32_e32 v148, v89, v141
	s_waitcnt lgkmcnt(0)
	v_fmac_f32_e32 v148, v86, v142
	v_fmac_f32_e32 v148, v85, v143
	v_fmac_f32_e32 v148, v87, v144
	v_fmac_f32_e32 v148, v90, v145
	v_mul_f32_e64 v138, |v148|, s84
	v_exp_f32_e32 v138, v138
	v_fmac_f32_e32 v147, 0x3377d1cf, v146
	v_fmac_f32_e32 v147, 0x3f317217, v146
	v_cmp_lt_f32_e64 s[38:39], |v146|, s87
	v_add_f32_e32 v138, 1.0, v138
	v_cndmask_b32_e32 v140, 0, v81, vcc
	v_cndmask_b32_e64 v139, v146, v147, s[38:39]
	v_cmp_gt_f32_e32 vcc, s85, v138
	v_sub_f32_e32 v139, v139, v140
	v_sub_f32_e32 v137, v137, v139
	v_cndmask_b32_e64 v140, 0, 32, vcc
	v_ldexp_f32 v138, v138, v140
	v_log_f32_e32 v146, v138
	ds_read_b128 v[138:141], v13 offset:832
	v_min_f32_e32 v147, 0, v148
	v_fmamk_f32 v136, v136, 0x3d800000, v135
	v_mul_f32_e32 v142, 0x3f317217, v146
	v_fma_f32 v148, v146, s86, -v142
	ds_read_b128 v[142:145], v13 offset:848
	s_waitcnt lgkmcnt(1)
	v_fma_f32 v149, v91, v138, v3
	v_fmac_f32_e32 v149, v0, v139
	v_fmac_f32_e32 v149, v83, v140
	v_fmac_f32_e32 v149, v84, v141
	ds_read_b128 v[138:141], v13 offset:864
	s_waitcnt lgkmcnt(1)
	v_fmac_f32_e32 v149, v53, v142
	v_fmac_f32_e32 v149, v4, v143
	v_fmac_f32_e32 v149, v5, v144
	v_fmac_f32_e32 v149, v51, v145
	ds_read_b128 v[142:145], v13 offset:880
	s_waitcnt lgkmcnt(1)
	v_fmac_f32_e32 v149, v1, v138
	v_fmac_f32_e32 v149, v2, v139
	v_fmac_f32_e32 v149, v88, v140
	v_fmac_f32_e32 v149, v89, v141
	s_waitcnt lgkmcnt(0)
	v_fmac_f32_e32 v149, v86, v142
	v_fmac_f32_e32 v149, v85, v143
	v_fmac_f32_e32 v149, v87, v144
	v_fmac_f32_e32 v149, v90, v145
	v_mul_f32_e64 v138, |v149|, s84
	v_exp_f32_e32 v138, v138
	v_fmac_f32_e32 v148, 0x3377d1cf, v146
	v_fmac_f32_e32 v148, 0x3f317217, v146
	v_cmp_lt_f32_e64 s[38:39], |v146|, s87
	v_add_f32_e32 v138, 1.0, v138
	v_cndmask_b32_e32 v140, 0, v81, vcc
	v_cndmask_b32_e64 v139, v146, v148, s[38:39]
	v_cmp_gt_f32_e32 vcc, s85, v138
	v_sub_f32_e32 v139, v139, v140
	v_fmamk_f32 v137, v137, 0x3d800000, v136
	v_cndmask_b32_e64 v140, 0, 32, vcc
	v_ldexp_f32 v138, v138, v140
	v_log_f32_e32 v148, v138
	ds_read_b128 v[140:143], v13 offset:896
	v_sub_f32_e32 v138, v147, v139
	v_min_f32_e32 v139, 0, v149
	v_mul_f32_e32 v144, 0x3f317217, v148
	v_fma_f32 v149, v148, s86, -v144
	ds_read_b128 v[144:147], v13 offset:912
	s_waitcnt lgkmcnt(1)
	v_fma_f32 v150, v91, v140, v3
	v_fmac_f32_e32 v150, v0, v141
	v_fmac_f32_e32 v150, v83, v142
	v_fmac_f32_e32 v150, v84, v143
	ds_read_b128 v[140:143], v13 offset:928
	s_waitcnt lgkmcnt(1)
	v_fmac_f32_e32 v150, v53, v144
	v_fmac_f32_e32 v150, v4, v145
	v_fmac_f32_e32 v150, v5, v146
	v_fmac_f32_e32 v150, v51, v147
	ds_read_b128 v[144:147], v13 offset:944
	s_waitcnt lgkmcnt(1)
	v_fmac_f32_e32 v150, v1, v140
	v_fmac_f32_e32 v150, v2, v141
	v_fmac_f32_e32 v150, v88, v142
	v_fmac_f32_e32 v150, v89, v143
	s_waitcnt lgkmcnt(0)
	v_fmac_f32_e32 v150, v86, v144
	v_fmac_f32_e32 v150, v85, v145
	v_fmac_f32_e32 v150, v87, v146
	v_fmac_f32_e32 v150, v90, v147
	v_mul_f32_e64 v140, |v150|, s84
	v_exp_f32_e32 v140, v140
	v_fmac_f32_e32 v149, 0x3377d1cf, v148
	v_fmac_f32_e32 v149, 0x3f317217, v148
	v_cmp_lt_f32_e64 s[38:39], |v148|, s87
	v_add_f32_e32 v140, 1.0, v140
	v_cndmask_b32_e32 v142, 0, v81, vcc
	v_cndmask_b32_e64 v141, v148, v149, s[38:39]
	v_cmp_gt_f32_e32 vcc, s85, v140
	v_sub_f32_e32 v141, v141, v142
	v_sub_f32_e32 v139, v139, v141
	v_cndmask_b32_e64 v142, 0, 32, vcc
	v_ldexp_f32 v140, v140, v142
	v_log_f32_e32 v148, v140
	ds_read_b128 v[140:143], v13 offset:960
	v_min_f32_e32 v149, 0, v150
	v_fmamk_f32 v138, v138, 0x3d800000, v137
	v_mul_f32_e32 v144, 0x3f317217, v148
	v_fma_f32 v150, v148, s86, -v144
	ds_read_b128 v[144:147], v13 offset:976
	s_waitcnt lgkmcnt(1)
	v_fmac_f32_e32 v3, v91, v140
	v_fmac_f32_e32 v3, v0, v141
	v_fmac_f32_e32 v3, v83, v142
	v_fmac_f32_e32 v3, v84, v143
	ds_read_b128 v[140:143], v13 offset:992
	s_waitcnt lgkmcnt(1)
	v_fmac_f32_e32 v3, v53, v144
	v_fmac_f32_e32 v3, v4, v145
	v_fmac_f32_e32 v3, v5, v146
	v_fmac_f32_e32 v3, v51, v147
	ds_read_b128 v[144:147], v13 offset:1008
	s_waitcnt lgkmcnt(1)
	v_fmac_f32_e32 v3, v1, v140
	v_fmac_f32_e32 v3, v2, v141
	v_fmac_f32_e32 v3, v88, v142
	v_fmac_f32_e32 v3, v89, v143
	s_waitcnt lgkmcnt(0)
	v_fmac_f32_e32 v3, v86, v144
	v_fmac_f32_e32 v3, v85, v145
	v_fmac_f32_e32 v3, v87, v146
	v_fmac_f32_e32 v3, v90, v147
	v_mul_f32_e64 v0, |v3|, s84
	v_exp_f32_e32 v0, v0
	v_fmac_f32_e32 v150, 0x3377d1cf, v148
	v_fmac_f32_e32 v150, 0x3f317217, v148
	v_cmp_lt_f32_e64 s[38:39], |v148|, s87
	v_add_f32_e32 v0, 1.0, v0
	v_cndmask_b32_e32 v2, 0, v81, vcc
	v_cndmask_b32_e64 v1, v148, v150, s[38:39]
	v_cmp_gt_f32_e32 vcc, s85, v0
	v_sub_f32_e32 v1, v1, v2
	v_fmamk_f32 v139, v139, 0x3d800000, v138
	v_cndmask_b32_e64 v2, 0, 32, vcc
	v_ldexp_f32 v0, v0, v2
	v_log_f32_e32 v0, v0
	v_sub_f32_e32 v1, v149, v1
	v_fmamk_f32 v51, v1, 0x3d800000, v139
	v_min_f32_e32 v1, 0, v3
	v_mul_f32_e32 v2, 0x3f317217, v0
	v_fma_f32 v2, v0, s86, -v2
	v_fmac_f32_e32 v2, 0x3377d1cf, v0
	v_fmac_f32_e32 v2, 0x3f317217, v0
	v_cmp_lt_f32_e64 s[38:39], |v0|, s87
	s_nop 1
	v_cndmask_b32_e64 v0, v0, v2, s[38:39]
	v_cndmask_b32_e32 v2, 0, v81, vcc
	v_sub_f32_e32 v0, v0, v2
	v_sub_f32_e32 v0, v1, v0
	v_fmamk_f32 v53, v0, 0x3d800000, v51
	ds_write_b32 v15, v53
	s_waitcnt lgkmcnt(0)
	s_barrier
	ds_read2st64_b32 v[2:3], v56 offset1:2
	ds_read2st64_b32 v[0:1], v56 offset0:4 offset1:6
	s_waitcnt lgkmcnt(1)
	v_add_f32_e32 v83, 0, v2
	v_add_f32_e32 v2, v83, v3
	s_waitcnt lgkmcnt(0)
	v_add_f32_e32 v2, v2, v0
	v_add_f32_e32 v2, v2, v1
	v_mul_f32_e32 v2, 0x3fb8aa3b, v2
	v_exp_f32_e32 v2, v2
	s_and_saveexec_b64 s[38:39], s[6:7]
	s_cbranch_execz .LBB0_644
	s_lshl_b64 s[92:93], s[58:59], 9
	v_lshl_add_u64 v[4:5], v[42:43], 0, s[92:93]
	global_store_dword v[4:5], v2, off sc1
.LBB0_644:
	s_or_b64 exec, exec, s[38:39]
	v_cndmask_b32_e64 v83, v83, 0, s[6:7]
	v_add_f32_e32 v3, v3, v83
	v_cndmask_b32_e64 v3, v83, v3, s[8:9]
	v_add_f32_e32 v0, v0, v3
	v_cndmask_b32_e64 v0, v3, v0, s[10:11]
	v_add_f32_e32 v1, v1, v0
	v_cndmask_b32_e64 v1, v0, v1, s[12:13]
	s_waitcnt vmcnt(7)
	v_lshlrev_b32_e32 v4, 16, v124
	v_add_f32_e32 v0, v125, v1
	v_mul_f32_e32 v124, 0x3db504f3, v4
	v_lshlrev_b32_e32 v4, 16, v102
	v_mul_f32_e32 v0, 0x3fb8aa3b, v0
	v_mul_f32_e32 v140, 0x3db504f3, v4
	v_lshlrev_b32_e32 v4, 16, v97
	v_add_f32_e32 v3, v126, v1
	v_exp_f32_e32 v83, v0
	v_mul_f32_e32 v97, 0x3db504f3, v4
	v_lshlrev_b32_e32 v4, 16, v98
	v_mul_f32_e32 v0, 0x3fb8aa3b, v3
	s_waitcnt vmcnt(6)
	v_lshlrev_b32_e32 v84, 16, v123
	v_mul_f32_e32 v123, 0x3db504f3, v4
	v_lshlrev_b32_e32 v4, 16, v94
	v_exp_f32_e32 v3, v0
	v_mul_f32_e32 v141, 0x3db504f3, v4
	v_lshlrev_b32_e32 v4, 16, v108
	v_mul_f32_e32 v108, 0x3db504f3, v4
	v_lshlrev_b32_e32 v4, 16, v105
	v_rcp_f32_e32 v102, v83
	v_lshlrev_b32_e32 v89, 16, v107
	v_mul_f32_e32 v107, 0x3db504f3, v4
	v_lshlrev_b32_e32 v4, 16, v106
	v_lshlrev_b32_e32 v85, 16, v101
	v_mul_f32_e32 v106, 0x3db504f3, v4
	v_lshlrev_b32_e32 v91, 16, v104
	v_lshlrev_b32_e32 v90, 16, v100
	v_lshlrev_b32_e32 v4, 16, v103
	v_lshl_add_u64 v[100:101], v[44:45], 0, s[52:53]
	v_rcp_f32_e32 v103, v3
	v_mul_f32_e32 v83, v124, v83
	v_mul_f32_e32 v3, v140, v3
	v_lshlrev_b64 v[104:105], 10, v[54:55]
	v_cvt_pk_bf16_f32 v83, v83, s0
	v_cvt_pk_bf16_f32 v3, v3, s0
	v_lshl_add_u64 v[104:105], v[100:101], 0, v[104:105]
	ds_write_b16 v57, v83
	ds_write_b16 v57, v3 offset:272
	global_store_short v[104:105], v83, off sc1
	global_store_short v[104:105], v3, off offset:1024 sc1
	v_mul_f32_e32 v3, v102, v84
	v_cvt_pk_bf16_f32 v3, v3, s0
	ds_write_b16 v57, v3 offset:17408
	v_mul_f32_e32 v3, v103, v85
	v_cvt_pk_bf16_f32 v3, v3, s0
	ds_write_b16 v57, v3 offset:17680
	v_pk_mul_f32 v[102:103], v[2:3], v[102:103] op_sel_hi:[0,1]
	v_add_f32_e32 v3, v127, v1
	v_mul_f32_e32 v3, 0x3fb8aa3b, v3
	v_add_f32_e32 v83, v128, v1
	v_exp_f32_e32 v3, v3
	v_mul_f32_e32 v83, 0x3fb8aa3b, v83
	v_exp_f32_e32 v83, v83
	v_pk_mul_f32 v[84:85], v[102:103], v[84:85]
	v_rcp_f32_e32 v102, v3
	v_lshl_add_u64 v[104:105], s[60:61], 0, v[20:21]
	v_rcp_f32_e32 v103, v83
	v_mul_f32_e32 v3, v97, v3
	v_lshlrev_b64 v[104:105], 10, v[104:105]
	v_lshlrev_b32_e32 v86, 16, v93
	v_cvt_pk_bf16_f32 v3, v3, s0
	v_mul_f32_e32 v83, v123, v83
	v_lshl_add_u64 v[104:105], v[100:101], 0, v[104:105]
	v_cvt_pk_bf16_f32 v83, v83, s0
	ds_write_b16 v58, v3
	ds_write_b16 v58, v83 offset:272
	global_store_short v[104:105], v3, off sc1
	global_store_short v[104:105], v83, off offset:1024 sc1
	v_mul_f32_e32 v3, v102, v86
	v_lshlrev_b32_e32 v87, 16, v95
	v_cvt_pk_bf16_f32 v3, v3, s0
	ds_write_b16 v58, v3 offset:17408
	v_mul_f32_e32 v3, v103, v87
	v_cvt_pk_bf16_f32 v3, v3, s0
	ds_write_b16 v58, v3 offset:17680
	v_pk_mul_f32 v[102:103], v[2:3], v[102:103] op_sel_hi:[0,1]
	v_add_f32_e32 v3, v129, v1
	v_mul_f32_e32 v3, 0x3fb8aa3b, v3
	v_add_f32_e32 v83, v130, v1
	v_exp_f32_e32 v3, v3
	v_mul_f32_e32 v83, 0x3fb8aa3b, v83
	v_exp_f32_e32 v83, v83
	v_pk_mul_f32 v[86:87], v[102:103], v[86:87]
	v_cvt_pk_bf16_f32 v84, v84, v85
	v_cvt_pk_bf16_f32 v85, v86, v87
	v_rcp_f32_e32 v86, v3
	v_lshl_add_u64 v[102:103], s[60:61], 0, v[22:23]
	v_rcp_f32_e32 v87, v83
	v_mul_f32_e32 v3, v141, v3
	v_lshlrev_b64 v[102:103], 10, v[102:103]
	v_lshlrev_b32_e32 v88, 16, v92
	v_cvt_pk_bf16_f32 v3, v3, s0
	v_mul_f32_e32 v83, v108, v83
	v_lshl_add_u64 v[102:103], v[100:101], 0, v[102:103]
	v_cvt_pk_bf16_f32 v83, v83, s0
	ds_write_b16 v59, v3
	ds_write_b16 v59, v83 offset:272
	global_store_short v[102:103], v3, off sc1
	global_store_short v[102:103], v83, off offset:1024 sc1
	v_mul_f32_e32 v3, v86, v88
	v_cvt_pk_bf16_f32 v3, v3, s0
	ds_write_b16 v59, v3 offset:17408
	v_mul_f32_e32 v3, v87, v89
	v_cvt_pk_bf16_f32 v3, v3, s0
	ds_write_b16 v59, v3 offset:17680
	v_pk_mul_f32 v[86:87], v[2:3], v[86:87] op_sel_hi:[0,1]
	v_add_f32_e32 v3, v131, v1
	v_mul_f32_e32 v3, 0x3fb8aa3b, v3
	v_add_f32_e32 v83, v132, v1
	v_exp_f32_e32 v3, v3
	v_mul_f32_e32 v83, 0x3fb8aa3b, v83
	v_exp_f32_e32 v83, v83
	v_pk_mul_f32 v[86:87], v[86:87], v[88:89]
	v_rcp_f32_e32 v88, v3
	v_lshl_add_u64 v[102:103], s[60:61], 0, v[24:25]
	v_rcp_f32_e32 v89, v83
	v_mul_f32_e32 v3, v107, v3
	v_lshlrev_b64 v[102:103], 10, v[102:103]
	v_cvt_pk_bf16_f32 v3, v3, s0
	v_mul_f32_e32 v83, v106, v83
	v_lshl_add_u64 v[102:103], v[100:101], 0, v[102:103]
	v_cvt_pk_bf16_f32 v83, v83, s0
	ds_write_b16 v60, v3
	ds_write_b16 v60, v83 offset:272
	global_store_short v[102:103], v3, off sc1
	global_store_short v[102:103], v83, off offset:1024 sc1
	v_mul_f32_e32 v3, v88, v90
	v_cvt_pk_bf16_f32 v3, v3, s0
	ds_write_b16 v60, v3 offset:17408
	v_mul_f32_e32 v3, v89, v91
	v_cvt_pk_bf16_f32 v3, v3, s0
	ds_write_b16 v60, v3 offset:17680
	v_pk_mul_f32 v[88:89], v[2:3], v[88:89] op_sel_hi:[0,1]
	v_add_f32_e32 v3, v133, v1
	v_mul_f32_e32 v3, 0x3fb8aa3b, v3
	v_add_f32_e32 v83, v135, v1
	v_exp_f32_e32 v3, v3
	v_mul_f32_e32 v83, 0x3fb8aa3b, v83
	v_exp_f32_e32 v83, v83
	v_pk_mul_f32 v[88:89], v[88:89], v[90:91]
	v_cvt_pk_bf16_f32 v86, v86, v87
	v_cvt_pk_bf16_f32 v87, v88, v89
	v_rcp_f32_e32 v88, v3
	v_mul_f32_e32 v142, 0x3db504f3, v4
	v_lshlrev_b32_e32 v4, 16, v116
	v_lshl_add_u64 v[90:91], s[60:61], 0, v[26:27]
	v_mul_f32_e32 v116, 0x3db504f3, v4
	v_rcp_f32_e32 v89, v83
	v_mul_f32_e32 v3, v142, v3
	v_lshlrev_b64 v[90:91], 10, v[90:91]
	v_lshlrev_b32_e32 v92, 16, v99
	v_cvt_pk_bf16_f32 v3, v3, s0
	v_mul_f32_e32 v83, v116, v83
	v_lshl_add_u64 v[90:91], v[100:101], 0, v[90:91]
	v_cvt_pk_bf16_f32 v83, v83, s0
	ds_write_b16 v61, v3
	ds_write_b16 v61, v83 offset:272
	global_store_short v[90:91], v3, off sc1
	global_store_short v[90:91], v83, off offset:1024 sc1
	v_mul_f32_e32 v3, v88, v92
	v_lshlrev_b32_e32 v93, 16, v115
	v_cvt_pk_bf16_f32 v3, v3, s0
	ds_write_b16 v61, v3 offset:17408
	v_mul_f32_e32 v3, v89, v93
	v_cvt_pk_bf16_f32 v3, v3, s0
	ds_write_b16 v61, v3 offset:17680
	v_pk_mul_f32 v[88:89], v[2:3], v[88:89] op_sel_hi:[0,1]
	v_add_f32_e32 v3, v136, v1
	v_mul_f32_e32 v3, 0x3fb8aa3b, v3
	v_add_f32_e32 v83, v137, v1
	v_exp_f32_e32 v3, v3
	v_mul_f32_e32 v83, 0x3fb8aa3b, v83
	v_exp_f32_e32 v83, v83
	v_lshlrev_b32_e32 v4, 16, v113
	v_rcp_f32_e32 v90, v3
	v_mul_f32_e32 v113, 0x3db504f3, v4
	v_lshlrev_b32_e32 v4, 16, v114
	v_pk_mul_f32 v[88:89], v[88:89], v[92:93]
	v_lshl_add_u64 v[92:93], s[60:61], 0, v[28:29]
	v_mul_f32_e32 v114, 0x3db504f3, v4
	v_rcp_f32_e32 v91, v83
	v_mul_f32_e32 v3, v113, v3
	v_lshlrev_b64 v[92:93], 10, v[92:93]
	v_lshlrev_b32_e32 v94, 16, v110
	v_cvt_pk_bf16_f32 v3, v3, s0
	v_mul_f32_e32 v83, v114, v83
	v_lshl_add_u64 v[92:93], v[100:101], 0, v[92:93]
	v_cvt_pk_bf16_f32 v83, v83, s0
	ds_write_b16 v62, v3
	ds_write_b16 v62, v83 offset:272
	global_store_short v[92:93], v3, off sc1
	global_store_short v[92:93], v83, off offset:1024 sc1
	v_mul_f32_e32 v3, v90, v94
	v_lshlrev_b32_e32 v95, 16, v112
	v_cvt_pk_bf16_f32 v3, v3, s0
	ds_write_b16 v62, v3 offset:17408
	v_mul_f32_e32 v3, v91, v95
	v_cvt_pk_bf16_f32 v3, v3, s0
	ds_write_b16 v62, v3 offset:17680
	v_pk_mul_f32 v[90:91], v[2:3], v[90:91] op_sel_hi:[0,1]
	v_add_f32_e32 v3, v138, v1
	v_mul_f32_e32 v3, 0x3fb8aa3b, v3
	v_add_f32_e32 v83, v139, v1
	v_exp_f32_e32 v3, v3
	v_mul_f32_e32 v83, 0x3fb8aa3b, v83
	v_exp_f32_e32 v83, v83
	v_pk_mul_f32 v[90:91], v[90:91], v[94:95]
	v_lshlrev_b32_e32 v4, 16, v111
	v_cvt_pk_bf16_f32 v88, v88, v89
	v_cvt_pk_bf16_f32 v89, v90, v91
	v_rcp_f32_e32 v90, v3
	v_mul_f32_e32 v110, 0x3db504f3, v4
	s_waitcnt vmcnt(17)
	v_lshlrev_b32_e32 v4, 16, v122
	v_lshl_add_u64 v[92:93], s[60:61], 0, v[30:31]
	v_mul_f32_e32 v111, 0x3db504f3, v4
	v_rcp_f32_e32 v91, v83
	v_mul_f32_e32 v3, v110, v3
	v_lshlrev_b64 v[92:93], 10, v[92:93]
	v_lshlrev_b32_e32 v98, 16, v109
	v_cvt_pk_bf16_f32 v3, v3, s0
	v_mul_f32_e32 v83, v111, v83
	v_lshl_add_u64 v[92:93], v[100:101], 0, v[92:93]
	v_cvt_pk_bf16_f32 v83, v83, s0
	ds_write_b16 v63, v3
	ds_write_b16 v63, v83 offset:272
	global_store_short v[92:93], v3, off sc1
	global_store_short v[92:93], v83, off offset:1024 sc1
	v_mul_f32_e32 v3, v90, v98
	s_waitcnt vmcnt(18)
	v_lshlrev_b32_e32 v99, 16, v121
	v_cvt_pk_bf16_f32 v3, v3, s0
	ds_write_b16 v63, v3 offset:17408
	v_mul_f32_e32 v3, v91, v99
	v_cvt_pk_bf16_f32 v3, v3, s0
	ds_write_b16 v63, v3 offset:17680
	v_pk_mul_f32 v[90:91], v[2:3], v[90:91] op_sel_hi:[0,1]
	v_add_f32_e32 v3, v51, v1
	v_add_f32_e32 v1, v53, v1
	v_mul_f32_e32 v3, 0x3fb8aa3b, v3
	v_exp_f32_e32 v3, v3
	v_mul_f32_e32 v1, 0x3fb8aa3b, v1
	v_exp_f32_e32 v1, v1
	s_waitcnt vmcnt(17)
	v_lshlrev_b32_e32 v4, 16, v118
	v_mul_f32_e32 v109, 0x3db504f3, v4
	s_waitcnt vmcnt(15)
	v_lshlrev_b32_e32 v4, 16, v119
	v_rcp_f32_e32 v92, v3
	v_mul_f32_e32 v112, 0x3db504f3, v4
	v_rcp_f32_e32 v93, v1
	v_lshl_add_u64 v[94:95], s[60:61], 0, v[32:33]
	v_mul_f32_e32 v3, v109, v3
	v_mul_f32_e32 v1, v112, v1
	v_lshlrev_b64 v[94:95], 10, v[94:95]
	v_lshlrev_b32_e32 v4, 16, v117
	v_cvt_pk_bf16_f32 v3, v3, s0
	v_cvt_pk_bf16_f32 v1, v1, s0
	v_lshl_add_u64 v[94:95], v[100:101], 0, v[94:95]
	ds_write_b16 v64, v3
	ds_write_b16 v64, v1 offset:272
	global_store_short v[94:95], v3, off sc1
	global_store_short v[94:95], v1, off offset:1024 sc1
	v_mul_f32_e32 v1, v92, v4
	s_waitcnt vmcnt(16)
	v_lshlrev_b32_e32 v5, 16, v120
	v_cvt_pk_bf16_f32 v1, v1, s0
	v_pk_mul_f32 v[2:3], v[2:3], v[92:93] op_sel_hi:[0,1]
	v_pk_mul_f32 v[90:91], v[90:91], v[98:99]
	ds_write_b16 v64, v1 offset:17408
	v_mul_f32_e32 v1, v93, v5
	v_pk_mul_f32 v[2:3], v[2:3], v[4:5]
	s_lshl_b64 s[38:39], s[58:59], 14
	v_cvt_pk_bf16_f32 v90, v90, v91
	v_cvt_pk_bf16_f32 v1, v1, s0
	v_cvt_pk_bf16_f32 v91, v2, v3
	v_lshl_add_u64 v[2:3], v[46:47], 0, s[38:39]
	v_mov_b32_e32 v0, 0
	ds_write_b16 v64, v1 offset:17680
	global_store_dwordx4 v[2:3], v[84:87], off sc1
	global_store_dwordx4 v[2:3], v[88:91], off offset:16 sc1
	v_mov_b32_e32 v2, 0
	v_mov_b32_e32 v3, 0
	v_mov_b32_e32 v4, 0
	v_mov_b32_e32 v5, 0
	s_waitcnt lgkmcnt(0)
	s_barrier
	s_and_saveexec_b64 s[38:39], s[14:15]
	s_cbranch_execz .LBB0_646
	ds_read_b128 v[2:5], v65
	ds_read_b128 v[84:87], v65 offset:64
	ds_read_b128 v[88:91], v82 offset:17408
	ds_read_b128 v[92:95], v82 offset:17472
	s_waitcnt lgkmcnt(1)
	v_mfma_f32_16x16x32_bf16 v[2:5], v[2:5], v[88:91], 0
	ds_read_b128 v[88:91], v65 offset:128
	ds_read_b128 v[98:101], v65 offset:192
	s_waitcnt lgkmcnt(2)
	v_mfma_f32_16x16x32_bf16 v[2:5], v[84:87], v[92:95], v[2:5]
	ds_read_b128 v[84:87], v82 offset:17536
	ds_read_b128 v[92:95], v82 offset:17600
	s_waitcnt lgkmcnt(1)
	v_mfma_f32_16x16x32_bf16 v[2:5], v[88:91], v[84:87], v[2:5]
	s_waitcnt lgkmcnt(0)
	v_mfma_f32_16x16x32_bf16 v[2:5], v[98:101], v[92:95], v[2:5]
